# v102 + no L2 write-back before the per-XCD arrivals (context residual tiles -> norm, attention -> out-proj context tiles): producer and consumer share the XCD's L2
# baseline (speedup 1.0000x reference)
; DI void grid_barrier(unsigned* cnt, unsigned target) {
;     asm volatile("s_waitcnt vmcnt(0) lgkmcnt(0)" ::: "memory");
;     __syncthreads();
;     if (threadIdx.x == 0) {
;         __builtin_amdgcn_fence(__ATOMIC_RELEASE, "agent");
;         asm volatile("s_waitcnt vmcnt(0)" ::: "memory");
;         __hip_atomic_fetch_add(cnt, 1u, __ATOMIC_RELAXED, __HIP_MEMORY_SCOPE_AGENT);
;         while (__hip_atomic_load(cnt, __ATOMIC_RELAXED, __HIP_MEMORY_SCOPE_AGENT) < target) __builtin_amdgcn_s_sleep(2);
;         __builtin_amdgcn_fence(__ATOMIC_ACQUIRE, "agent");
;         asm volatile("s_waitcnt vmcnt(0)" ::: "memory");
;     }
;     __syncthreads();
; }
.LBB0_579:
	s_cmp_eq_u32 s98, 1
	s_cbranch_scc0 .Lcs_b_normal
	s_add_u32 s100, s100, 1
	s_mov_b32 s98, 2
	v_readlane_b32 s2, v255, 0
	s_cmp_lt_u32 s2, 64
	s_cbranch_scc0 .LBB0_585
	s_waitcnt vmcnt(0) lgkmcnt(0)
	s_barrier
	s_mov_b64 s[4:5], exec
	v_readlane_b32 s2, v255, 3
	v_readlane_b32 s3, v255, 4
	s_and_b64 s[2:3], s[4:5], s[2:3]
	s_mov_b64 exec, s[2:3]
	s_cbranch_execz .Lcs_b_arrdone
	v_mov_b32_e32 v0, 1
	v_readlane_b32 s2, v255, 0
	s_and_b32 s2, s2, 7
	s_lshl_b32 s2, s2, 2
	s_add_u32 s2, s14, s2
	s_addc_u32 s3, s15, 0
	global_atomic_add v1, v0, s[2:3] offset:64

; DI const float* in_ptr(const Args& AR, int i) { asm volatile("" : "+s"(i)); return GLOBAL_PTR(const float, AR.in[i]); }
; #define GRID_SYNC() do { nbar += (unsigned)gridDim.x; grid_barrier(barw, nbar); } while (0)
; __global__ void __launch_bounds__(512, 2) fwd_megakernel(Args args) {
;     ...
;             } else if (type == T_ATTE) {
;                 if (PM & 1024) { const float* qg_ = in_ptr(AR, 11) + li * 128; attn_even_lds(F, in_ptr(AR, 12) + (size_t)li * 12 * 465, qg_ + 64, qg_); attn_evenctx_lds(F, qg_ + 64, qg_); }
;             } else if (type == T_ATTO) {
;                 if (PM & 2048) { const float* qg_ = in_ptr(AR, 15) + li * 128; attn_odd_lds(F, qg_ + 64, qg_, l < 3); }
;             }
;             if (!(op == 4 || op == 6 || op == 7 || skip0)) GRID_SYNC();
.Lxl_pre:
	s_waitcnt lgkmcnt(0)
	s_cmp_eq_u32 s13, 0x100
	s_cbranch_scc0 .Lxl_no
	s_cmp_eq_u32 s44, 9
	s_cbranch_scc0 .Lat_not9
	s_waitcnt vmcnt(0) lgkmcnt(0)
	s_barrier
	v_readlane_b32 s10, v255, 63
	s_add_u32 s10, s10, 1
	s_nop 0
	v_writelane_b32 v255, s10, 63
	s_mov_b64 s[4:5], exec
	v_readlane_b32 s6, v255, 3
	v_readlane_b32 s7, v255, 4
	s_and_b64 s[6:7], s[4:5], s[6:7]
	s_mov_b64 exec, s[6:7]
	s_cbranch_execz .Lar_E
	v_mov_b32_e32 v0, 1
	v_readlane_b32 s2, v255, 0
	s_and_b32 s2, s2, 7
	s_lshl_b32 s2, s2, 2
	s_add_u32 s8, s14, s2
	s_addc_u32 s9, s15, 0
	global_atomic_add v1, v0, s[8:9] offset:208
	global_atomic_add v1, v0, s[14:15] offset:200
